# stream unit: loads re-issued behind each converted group (scalar base + lane offset), page table in SGPRs, per-workgroup 8KB in-page phase; plus attention selfmax removal
# speedup vs baseline: 1.0033x; 1.0033x over previous
.LBB0_538:
	s_or_b64 exec, exec, s[0:1]
	s_ashr_i32 s7, s20, 3
	s_ashr_i32 s4, s23, 8
	s_and_b32 s94, s20, 31
	s_lshl_b32 s94, s94, 13
	s_lshl_b32 s0, s7, 6
	s_ashr_i32 s1, s0, 31
	s_lshl_b32 s26, s4, 2
	s_and_b32 s6, s20, 7
	s_ashr_i32 s27, s26, 31
	s_lshl_b64 s[0:1], s[0:1], 2
	s_add_u32 s0, s76, s0
	s_addc_u32 s1, s77, s1
	s_lshl_b32 s23, s6, 5
	s_add_u32 s23, s0, s23
	s_addc_u32 s28, s1, 0
	s_lshl_b32 s0, s22, 14
	s_add_i32 s25, s0, 0
	s_lshl_b64 s[0:1], s[26:27], 2
	s_add_u32 s0, s23, s0
	s_addc_u32 s1, s28, s1
	s_load_dwordx2 s[98:99], s[0:1], 0x0
	s_load_dwordx2 s[100:101], s[0:1], 0x8
	global_load_dword v18, v183, s[0:1]
	v_bfe_u32 v19, v20, 4, 2
	v_and_b32_e32 v192, 63, v20
	v_lshlrev_b32_e32 v103, 3, v20
	v_lshrrev_b32_e32 v21, 2, v190
	v_lshlrev_b32_e32 v191, 2, v19
	s_waitcnt vmcnt(39)
	v_xor_b32_e32 v22, v19, v190
	v_bitop3_b32 v23, v19, v190, 4 bitop3:0x36
	v_bitop3_b32 v24, v19, v190, 8 bitop3:0x36
	v_bitop3_b32 v25, v19, v190, 12 bitop3:0x36
	v_and_b32_e32 v105, 24, v103
	v_lshrrev_b32_e32 v182, 5, v192
	v_or_b32_e32 v19, v191, v21
	v_lshl_or_b32 v122, v19, 8, v105
	v_lshlrev_b32_e32 v19, 5, v19
	s_movk_i32 s23, 0xe0
	v_and_b32_e32 v123, 0xe0, v19
	v_bitop3_b32 v124, v19, s23, v122 bitop3:0x26
	v_and_b32_e32 v102, 31, v20
	v_bfe_u32 v104, v20, 2, 3
	v_lshlrev_b32_e32 v20, 8, v190
	v_lshl_or_b32 v114, v22, 4, v20
	v_lshl_or_b32 v115, v23, 4, v20
	v_lshl_or_b32 v116, v24, 4, v20
	v_lshl_or_b32 v117, v25, 4, v20
	v_or_b32_e32 v178, 10, v182
	v_lshl_add_u32 v181, v178, 8, s25
	v_lshlrev_b32_e32 v184, 4, v178
	v_bitop3_b32 v178, v178, v104, 3 bitop3:0x6c
	v_lshl_add_u32 v205, v178, 5, v181
	v_or_b32_e32 v178, 12, v182
	v_bitop3_b32 v186, v184, v103, s19 bitop3:0x78
	v_lshl_add_u32 v206, v178, 8, s25
	v_lshlrev_b32_e32 v184, 4, v178
	v_bitop3_b32 v178, v178, v104, 5 bitop3:0x6c
	v_lshl_add_u32 v208, v178, 5, v206
	v_or_b32_e32 v178, 14, v182
	v_or_b32_e32 v131, 4, v182
	v_or_b32_e32 v134, 6, v182
	v_or_b32_e32 v137, 8, v182
	v_bitop3_b32 v207, v184, v103, s19 bitop3:0x78
	v_lshl_add_u32 v209, v178, 8, s25
	v_lshlrev_b32_e32 v184, 4, v178
	v_bitop3_b32 v178, v178, v104, 7 bitop3:0x6c
	v_lshl_add_u32 v132, v131, 8, s25
	v_lshlrev_b32_e32 v131, 4, v131
	v_lshl_add_u32 v135, v134, 8, s25
	v_lshlrev_b32_e32 v134, 4, v134
	v_lshl_add_u32 v179, v137, 8, s25
	v_lshlrev_b32_e32 v137, 4, v137
	v_lshl_add_u32 v210, v178, 5, v209
	v_or_b32_e32 v178, 18, v182
	v_bitop3_b32 v131, v131, v103, s19 bitop3:0x78
	v_bitop3_b32 v134, v134, v103, s19 bitop3:0x78
	v_bitop3_b32 v137, v137, v103, s19 bitop3:0x78
	v_lshl_add_u32 v211, v178, 8, s25
	s_movk_i32 s23, 0x60
	v_bitop3_b32 v127, v123, s23, v122 bitop3:0x36
	s_movk_i32 s23, 0x80
	v_bitop3_b32 v128, v123, s23, v122 bitop3:0x36
	s_movk_i32 s23, 0xa0
	v_bitop3_b32 v129, v123, s23, v122 bitop3:0x36
	s_movk_i32 s23, 0xc0
	v_bitop3_b32 v133, v182, v104, 4 bitop3:0x36
	v_bitop3_b32 v136, v182, v104, 6 bitop3:0x36
	v_bitop3_b32 v125, v123, 32, v122 bitop3:0x36
	v_bitop3_b32 v126, v123, 64, v122 bitop3:0x36
	v_bitop3_b32 v130, v123, s23, v122 bitop3:0x36
	s_lshl_b32 s23, s21, 7
	v_lshl_add_u32 v133, v133, 5, v132
	v_lshl_add_u32 v136, v136, 5, v135
	v_add_u32_e32 v123, s25, v123
	s_mov_b32 s22, 32
	v_add_u32_e32 v198, v132, v131
	v_add_u32_e32 v199, v133, v105
	v_add_u32_e32 v200, v135, v134
	v_add_u32_e32 v201, v136, v105
	v_add_u32_e32 v202, v179, v137
	v_add_u32_e32 v204, v181, v186
	v_add_u32_e32 v205, v205, v105
	s_waitcnt vmcnt(0)
	v_readfirstlane_b32 s26, v18
	s_ashr_i32 s27, s26, 31
	s_lshl_b64 s[26:27], s[26:27], 9
	v_lshl_or_b32 v18, v182, 2, s26
	v_mov_b32_e32 v19, s27
	v_or_b32_e32 v18, s21, v18
	v_lshlrev_b64 v[18:19], 9, v[18:19]
	v_lshl_or_b32 v18, v102, 4, v18
	v_lshl_add_u64 v[94:95], s[72:73], 0, v[18:19]
	v_add_co_u32_e32 v30, vcc, s11, v94
	v_lshl_add_u64 v[96:97], s[74:75], 0, v[18:19]
	s_nop 0
	v_addc_co_u32_e32 v31, vcc, 0, v95, vcc
	v_add_co_u32_e32 v38, vcc, s11, v96
	v_addc_co_u32_e32 v39, vcc, 0, v97, vcc
	v_add_co_u32_e32 v46, vcc, s10, v94
	s_movk_i32 s26, 0x50
	s_nop 0
	v_addc_co_u32_e32 v47, vcc, 0, v95, vcc
	v_add_co_u32_e32 v54, vcc, s10, v96
	v_add_u32_e32 v206, v206, v207
	s_nop 0
	v_addc_co_u32_e32 v55, vcc, 0, v97, vcc
	v_add_co_u32_e32 v62, vcc, s12, v94
	v_add_u32_e32 v207, v208, v105
	s_nop 0
	v_addc_co_u32_e32 v63, vcc, 0, v95, vcc
	v_add_co_u32_e32 v70, vcc, s12, v96
	v_add_u32_e32 v234, s25, v125
	s_nop 0
	v_addc_co_u32_e32 v71, vcc, 0, v97, vcc
	v_add_co_u32_e32 v78, vcc, s13, v94
	s_nop 0
	s_nop 0
	s_nop 0
	s_nop 0
	s_nop 0
	s_nop 0
	s_nop 0
	s_nop 0
	s_nop 0
	s_nop 0
	s_nop 0
	v_addc_co_u32_e32 v79, vcc, 0, v95, vcc
	v_add_co_u32_e32 v86, vcc, s13, v96
	v_add_u32_e32 v235, s25, v126
	s_nop 0
	v_addc_co_u32_e32 v87, vcc, 0, v97, vcc
	v_add_co_u32_e32 v98, vcc, s14, v94
	s_nop 0
	s_nop 0
	s_nop 0
	v_addc_co_u32_e32 v99, vcc, 0, v95, vcc
	v_add_co_u32_e32 v100, vcc, s14, v96
	v_add_u32_e32 v236, s25, v127
	s_nop 0
	v_addc_co_u32_e32 v101, vcc, 0, v97, vcc
	v_add_co_u32_e32 v98, vcc, s15, v94
	v_add_u32_e32 v237, s25, v128
	s_nop 0
	v_addc_co_u32_e32 v99, vcc, 0, v95, vcc
	v_add_co_u32_e32 v100, vcc, s15, v96
	v_add_u32_e32 v238, s25, v129
	s_nop 0
	v_addc_co_u32_e32 v101, vcc, 0, v97, vcc
	v_add_co_u32_e32 v98, vcc, s17, v94
	v_add_u32_e32 v239, s25, v130
	s_nop 0
	v_addc_co_u32_e32 v99, vcc, 0, v95, vcc
	v_add_co_u32_e32 v100, vcc, s17, v96
	v_add_u32_e32 v240, s25, v124
	s_nop 0
	v_addc_co_u32_e32 v101, vcc, 0, v97, vcc
	v_add_co_u32_e32 v94, vcc, s18, v94
	v_addc_co_u32_e32 v95, vcc, 0, v95, vcc
	v_add_co_u32_e32 v94, vcc, s18, v96
	v_or_b32_e32 v99, 2, v182
	s_nop 0
	v_addc_co_u32_e32 v95, vcc, 0, v97, vcc
	v_lshlrev_b32_e32 v96, 4, v182
	v_lshl_add_u32 v100, v99, 8, s25
	v_lshlrev_b32_e32 v99, 4, v99
	v_and_b32_e32 v94, 0xf8, v103
	v_bitop3_b32 v96, v103, v96, s19 bitop3:0x6c
	v_bitop3_b32 v99, v99, v103, s19 bitop3:0x78
	v_bitop3_b32 v103, v184, v103, s19 bitop3:0x78
	v_lshlrev_b32_e32 v184, 4, v178
	v_bitop3_b32 v178, v178, v104, 3 bitop3:0x6c
	v_lshl_add_u32 v213, v178, 5, v211
	v_or_b32_e32 v178, 20, v182
	v_bitop3_b32 v212, v184, v94, 48 bitop3:0x6c
	v_lshl_add_u32 v214, v178, 8, s25
	v_lshlrev_b32_e32 v184, 4, v178
	v_bitop3_b32 v178, v178, v104, 5 bitop3:0x6c
	v_lshl_add_u32 v216, v178, 5, v214
	v_or_b32_e32 v178, 22, v182
	v_bitop3_b32 v215, v184, v94, s26 bitop3:0x6c
	v_lshl_add_u32 v217, v178, 8, s25
	v_lshlrev_b32_e32 v184, 4, v178
	v_bitop3_b32 v178, v178, v104, 7 bitop3:0x6c
	s_movk_i32 s26, 0x70
	v_lshl_add_u32 v219, v178, 5, v217
	v_or_b32_e32 v178, 24, v182
	v_bitop3_b32 v218, v184, v94, s26 bitop3:0x6c
	v_lshl_add_u32 v220, v178, 8, s25
	v_lshlrev_b32_e32 v178, 4, v178
	s_movk_i32 s26, 0x90
	v_bitop3_b32 v221, v178, v94, s26 bitop3:0x6c
	v_or_b32_e32 v178, 26, v182
	v_lshl_add_u32 v227, v178, 8, s25
	v_lshlrev_b32_e32 v184, 4, v178
	v_bitop3_b32 v178, v178, v104, 3 bitop3:0x6c
	s_movk_i32 s26, 0xb0
	v_lshl_add_u32 v229, v178, 5, v227
	v_or_b32_e32 v178, 28, v182
	v_bitop3_b32 v228, v184, v94, s26 bitop3:0x6c
	v_lshl_add_u32 v230, v178, 8, s25
	v_lshlrev_b32_e32 v184, 4, v178
	v_bitop3_b32 v178, v178, v104, 5 bitop3:0x6c
	v_xor_b32_e32 v97, v182, v104
	s_movk_i32 s26, 0xd0
	v_lshl_add_u32 v232, v178, 5, v230
	v_or_b32_e32 v178, 30, v182
	v_lshl_add_u32 v95, v182, 8, s25
	v_lshlrev_b32_e32 v97, 5, v97
	v_bitop3_b32 v101, v182, v104, 2 bitop3:0x36
	v_bitop3_b32 v231, v184, v94, s26 bitop3:0x6c
	v_lshl_add_u32 v233, v178, 8, s25
	v_lshlrev_b32_e32 v184, 4, v178
	s_movk_i32 s26, 0xf0
	v_bitop3_b32 v104, v178, v104, 7 bitop3:0x6c
	v_add_u32_e32 v98, v95, v97
	v_lshl_add_u32 v101, v101, 5, v100
	v_add_u32_e32 v180, v179, v97
	v_add_u32_e32 v97, v220, v97
	v_bitop3_b32 v94, v184, v94, s26 bitop3:0x6c
	v_lshl_add_u32 v104, v104, 5, v233
	v_lshl_or_b32 v184, v102, 2, s23
	v_lshlrev_b32_e32 v184, 2, v184
	v_lshl_or_b32 v184, v182, 11, v184
	v_mov_b32_e32 v178, 0xf149f2ca
	v_add_u32_e32 v194, v95, v96
	v_add_u32_e32 v195, v98, v105
	v_add_u32_e32 v196, v100, v99
	v_add_u32_e32 v197, v101, v105
	v_add_u32_e32 v203, v180, v105
	v_add_u32_e32 v208, v209, v103
	v_add_u32_e32 v209, v210, v105
	v_add_u32_e32 v210, v211, v212
	v_add_u32_e32 v211, v213, v105
	v_add_u32_e32 v212, v214, v215
	v_add_u32_e32 v213, v216, v105
	v_add_u32_e32 v214, v217, v218
	v_add_u32_e32 v215, v219, v105
	v_add_u32_e32 v216, v220, v221
	v_add_u32_e32 v217, v97, v105
	v_add_u32_e32 v218, v227, v228
	v_add_u32_e32 v219, v229, v105
	v_add_u32_e32 v220, v230, v231
	v_add_u32_e32 v221, v232, v105
	v_add_u32_e32 v227, v233, v94
	v_add_u32_e32 v228, v104, v105
	s_lshl_b32 s23, s23, 2
	v_add_u32_e32 v229, s25, v114
	v_add_u32_e32 v230, s25, v115
	v_add_u32_e32 v231, s25, v116
	v_add_u32_e32 v232, s25, v117
	v_add_u32_e32 v233, v123, v122
	v_mov_b32_e32 v94, 0
	v_mov_b32_e32 v95, v193
	v_mov_b32_e32 v96, v193
	v_mov_b32_e32 v97, v193
	v_mov_b32_e32 v98, 0
	v_mov_b32_e32 v99, v193
	v_mov_b32_e32 v100, v193
	v_mov_b32_e32 v101, v193
	v_mov_b32_e32 v102, 0
	v_mov_b32_e32 v103, v193
	v_mov_b32_e32 v104, v193
	v_mov_b32_e32 v105, v193
	v_mov_b32_e32 v114, 0
	v_mov_b32_e32 v115, v193
	v_mov_b32_e32 v116, v193
	v_mov_b32_e32 v117, v193
	v_mov_b32_e32 v122, 0
	v_mov_b32_e32 v123, v193
	v_mov_b32_e32 v124, v193
	v_mov_b32_e32 v125, v193
	v_mov_b32_e32 v126, 0
	v_mov_b32_e32 v127, v193
	v_mov_b32_e32 v128, v193
	v_mov_b32_e32 v129, v193
	v_mov_b32_e32 v130, 0
	v_mov_b32_e32 v131, v193
	v_mov_b32_e32 v132, v193
	v_mov_b32_e32 v133, v193
	v_mov_b32_e32 v134, 0
	v_mov_b32_e32 v135, v193
	v_mov_b32_e32 v136, v193
	v_mov_b32_e32 v137, v193
	s_waitcnt lgkmcnt(0)
	s_lshl_b32 s95, s98, 18
	s_add_u32 s95, s95, 0x1000
	s_add_u32 s30, s95, s94
	s_add_u32 s26, s72, s30
	s_addc_u32 s27, s73, 0
	s_add_u32 s28, s74, s30
	s_addc_u32 s29, s75, 0
	s_add_u32 s94, s94, 0x2000
	s_and_b32 s94, s94, 0x3ffff
	global_load_dwordx4 v[18:21], v184, s[26:27] offset:-4096 nt
	global_load_dwordx4 v[22:25], v184, s[28:29] offset:-4096 nt
	global_load_dwordx4 v[26:29], v184, s[26:27] nt
	global_load_dwordx4 v[34:37], v184, s[28:29] nt
	s_add_u32 s30, s95, s94
	s_add_u32 s26, s72, s30
	s_addc_u32 s27, s73, 0
	s_add_u32 s28, s74, s30
	s_addc_u32 s29, s75, 0
	s_add_u32 s94, s94, 0x2000
	s_and_b32 s94, s94, 0x3ffff
	global_load_dwordx4 v[30:33], v184, s[26:27] offset:-4096 nt
	global_load_dwordx4 v[38:41], v184, s[28:29] offset:-4096 nt
	global_load_dwordx4 v[42:45], v184, s[26:27] nt
	global_load_dwordx4 v[50:53], v184, s[28:29] nt
	s_add_u32 s30, s95, s94
	s_add_u32 s26, s72, s30
	s_addc_u32 s27, s73, 0
	s_add_u32 s28, s74, s30
	s_addc_u32 s29, s75, 0
	s_add_u32 s94, s94, 0x2000
	s_and_b32 s94, s94, 0x3ffff
	global_load_dwordx4 v[46:49], v184, s[26:27] offset:-4096 nt
	global_load_dwordx4 v[54:57], v184, s[28:29] offset:-4096 nt
	global_load_dwordx4 v[58:61], v184, s[26:27] nt
	global_load_dwordx4 v[66:69], v184, s[28:29] nt
	s_add_u32 s30, s95, s94
	s_add_u32 s26, s72, s30
	s_addc_u32 s27, s73, 0
	s_add_u32 s28, s74, s30
	s_addc_u32 s29, s75, 0
	s_add_u32 s94, s94, 0x2000
	s_and_b32 s94, s94, 0x3ffff
	global_load_dwordx4 v[62:65], v184, s[26:27] offset:-4096 nt
	global_load_dwordx4 v[70:73], v184, s[28:29] offset:-4096 nt
	global_load_dwordx4 v[74:77], v184, s[26:27] nt
	global_load_dwordx4 v[82:85], v184, s[28:29] nt
	s_add_u32 s30, s95, s94
	s_add_u32 s26, s72, s30
	s_addc_u32 s27, s73, 0
	s_add_u32 s28, s74, s30
	s_addc_u32 s29, s75, 0
	s_add_u32 s94, s94, 0x2000
	s_and_b32 s94, s94, 0x3ffff
	global_load_dwordx4 v[78:81], v184, s[26:27] offset:-4096 nt
	global_load_dwordx4 v[86:89], v184, s[28:29] offset:-4096 nt
	global_load_dwordx4 v[90:93], v184, s[26:27] nt
	global_load_dwordx4 v[110:113], v184, s[28:29] nt
	s_add_u32 s30, s95, s94
	s_add_u32 s26, s72, s30
	s_addc_u32 s27, s73, 0
	s_add_u32 s28, s74, s30
	s_addc_u32 s29, s75, 0
	s_add_u32 s94, s94, 0x2000
	s_and_b32 s94, s94, 0x3ffff
	global_load_dwordx4 v[106:109], v184, s[26:27] offset:-4096 nt
	global_load_dwordx4 v[118:121], v184, s[28:29] offset:-4096 nt
	global_load_dwordx4 v[138:141], v184, s[26:27] nt
	global_load_dwordx4 v[142:145], v184, s[28:29] nt
	s_add_u32 s30, s95, s94
	s_add_u32 s26, s72, s30
	s_addc_u32 s27, s73, 0
	s_add_u32 s28, s74, s30
	s_addc_u32 s29, s75, 0
	s_add_u32 s94, s94, 0x2000
	s_and_b32 s94, s94, 0x3ffff
	global_load_dwordx4 v[146:149], v184, s[26:27] offset:-4096 nt
	global_load_dwordx4 v[150:153], v184, s[28:29] offset:-4096 nt
	global_load_dwordx4 v[154:157], v184, s[26:27] nt
	global_load_dwordx4 v[158:161], v184, s[28:29] nt
	s_add_u32 s30, s95, s94
	s_add_u32 s26, s72, s30
	s_addc_u32 s27, s73, 0
	s_add_u32 s28, s74, s30
	s_addc_u32 s29, s75, 0
	s_add_u32 s94, s94, 0x2000
	s_and_b32 s94, s94, 0x3ffff
	global_load_dwordx4 v[162:165], v184, s[26:27] offset:-4096 nt
	global_load_dwordx4 v[166:169], v184, s[28:29] offset:-4096 nt
	global_load_dwordx4 v[170:173], v184, s[26:27] nt
	global_load_dwordx4 v[174:177], v184, s[28:29] nt
.LBB0_539:
	s_cmp_eq_u32 s24, 15
	s_cbranch_scc1 .Lsp_last_a
	s_add_i32 s25, s24, 1
	s_lshr_b32 s30, s25, 2
	s_cmp_lt_u32 s30, 2
	s_cselect_b32 s95, s98, s100
	s_cselect_b32 s97, s99, s101
	s_bitcmp1_b32 s30, 0
	s_cselect_b32 s95, s97, s95
	s_lshl_b32 s95, s95, 18
	s_add_u32 s95, s95, 0x1000
	s_waitcnt vmcnt(28)
	v_cvt_pk_bf16_f32 v244, v18, v19
	v_cvt_pk_bf16_f32 v245, v20, v21
	ds_write_b64 v194, v[244:245]
	v_cvt_pk_bf16_f32 v180, v22, v23
	v_cvt_pk_bf16_f32 v181, v24, v25
	ds_write_b64 v195, v[180:181] offset:8192
	v_cvt_pk_bf16_f32 v244, v26, v27
	v_cvt_pk_bf16_f32 v245, v28, v29
	ds_write_b64 v196, v[244:245]
	v_cvt_pk_bf16_f32 v180, v34, v35
	v_cvt_pk_bf16_f32 v181, v36, v37
	ds_write_b64 v197, v[180:181] offset:8192
	s_add_u32 s30, s95, s94
	s_add_u32 s26, s72, s30
	s_addc_u32 s27, s73, 0
	s_add_u32 s28, s74, s30
	s_addc_u32 s29, s75, 0
	s_add_u32 s94, s94, 0x2000
	s_and_b32 s94, s94, 0x3ffff
	global_load_dwordx4 v[18:21], v184, s[26:27] offset:-4096 nt
	global_load_dwordx4 v[22:25], v184, s[28:29] offset:-4096 nt
	global_load_dwordx4 v[26:29], v184, s[26:27] nt
	global_load_dwordx4 v[34:37], v184, s[28:29] nt
	s_waitcnt vmcnt(28)
	v_cvt_pk_bf16_f32 v244, v30, v31
	v_cvt_pk_bf16_f32 v245, v32, v33
	ds_write_b64 v198, v[244:245]
	v_cvt_pk_bf16_f32 v180, v38, v39
	v_cvt_pk_bf16_f32 v181, v40, v41
	ds_write_b64 v199, v[180:181] offset:8192
	v_cvt_pk_bf16_f32 v244, v42, v43
	v_cvt_pk_bf16_f32 v245, v44, v45
	ds_write_b64 v200, v[244:245]
	v_cvt_pk_bf16_f32 v180, v50, v51
	v_cvt_pk_bf16_f32 v181, v52, v53
	ds_write_b64 v201, v[180:181] offset:8192
	s_add_u32 s30, s95, s94
	s_add_u32 s26, s72, s30
	s_addc_u32 s27, s73, 0
	s_add_u32 s28, s74, s30
	s_addc_u32 s29, s75, 0
	s_add_u32 s94, s94, 0x2000
	s_and_b32 s94, s94, 0x3ffff
	global_load_dwordx4 v[30:33], v184, s[26:27] offset:-4096 nt
	global_load_dwordx4 v[38:41], v184, s[28:29] offset:-4096 nt
	global_load_dwordx4 v[42:45], v184, s[26:27] nt
	global_load_dwordx4 v[50:53], v184, s[28:29] nt
	s_waitcnt vmcnt(28)
	v_cvt_pk_bf16_f32 v244, v46, v47
	v_cvt_pk_bf16_f32 v245, v48, v49
	ds_write_b64 v202, v[244:245]
	v_cvt_pk_bf16_f32 v180, v54, v55
	v_cvt_pk_bf16_f32 v181, v56, v57
	ds_write_b64 v203, v[180:181] offset:8192
	v_cvt_pk_bf16_f32 v244, v58, v59
	v_cvt_pk_bf16_f32 v245, v60, v61
	ds_write_b64 v204, v[244:245]
	v_cvt_pk_bf16_f32 v180, v66, v67
	v_cvt_pk_bf16_f32 v181, v68, v69
	ds_write_b64 v205, v[180:181] offset:8192
	s_add_u32 s30, s95, s94
	s_add_u32 s26, s72, s30
	s_addc_u32 s27, s73, 0
	s_add_u32 s28, s74, s30
	s_addc_u32 s29, s75, 0
	s_add_u32 s94, s94, 0x2000
	s_and_b32 s94, s94, 0x3ffff
	global_load_dwordx4 v[46:49], v184, s[26:27] offset:-4096 nt
	global_load_dwordx4 v[54:57], v184, s[28:29] offset:-4096 nt
	global_load_dwordx4 v[58:61], v184, s[26:27] nt
	global_load_dwordx4 v[66:69], v184, s[28:29] nt
	s_waitcnt vmcnt(28)
	v_cvt_pk_bf16_f32 v244, v62, v63
	v_cvt_pk_bf16_f32 v245, v64, v65
	ds_write_b64 v206, v[244:245]
	v_cvt_pk_bf16_f32 v180, v70, v71
	v_cvt_pk_bf16_f32 v181, v72, v73
	ds_write_b64 v207, v[180:181] offset:8192
	v_cvt_pk_bf16_f32 v244, v74, v75
	v_cvt_pk_bf16_f32 v245, v76, v77
	ds_write_b64 v208, v[244:245]
	v_cvt_pk_bf16_f32 v180, v82, v83
	v_cvt_pk_bf16_f32 v181, v84, v85
	ds_write_b64 v209, v[180:181] offset:8192
	s_add_u32 s30, s95, s94
	s_add_u32 s26, s72, s30
	s_addc_u32 s27, s73, 0
	s_add_u32 s28, s74, s30
	s_addc_u32 s29, s75, 0
	s_add_u32 s94, s94, 0x2000
	s_and_b32 s94, s94, 0x3ffff
	global_load_dwordx4 v[62:65], v184, s[26:27] offset:-4096 nt
	global_load_dwordx4 v[70:73], v184, s[28:29] offset:-4096 nt
	global_load_dwordx4 v[74:77], v184, s[26:27] nt
	global_load_dwordx4 v[82:85], v184, s[28:29] nt
	s_waitcnt vmcnt(28)
	v_cvt_pk_bf16_f32 v244, v78, v79
	v_cvt_pk_bf16_f32 v245, v80, v81
	ds_write_b64 v194, v[244:245] offset:4096
	v_cvt_pk_bf16_f32 v180, v86, v87
	v_cvt_pk_bf16_f32 v181, v88, v89
	ds_write_b64 v195, v[180:181] offset:12288
	v_cvt_pk_bf16_f32 v244, v90, v91
	v_cvt_pk_bf16_f32 v245, v92, v93
	ds_write_b64 v210, v[244:245]
	v_cvt_pk_bf16_f32 v180, v110, v111
	v_cvt_pk_bf16_f32 v181, v112, v113
	ds_write_b64 v211, v[180:181] offset:8192
	s_add_u32 s30, s95, s94
	s_add_u32 s26, s72, s30
	s_addc_u32 s27, s73, 0
	s_add_u32 s28, s74, s30
	s_addc_u32 s29, s75, 0
	s_add_u32 s94, s94, 0x2000
	s_and_b32 s94, s94, 0x3ffff
	global_load_dwordx4 v[78:81], v184, s[26:27] offset:-4096 nt
	global_load_dwordx4 v[86:89], v184, s[28:29] offset:-4096 nt
	global_load_dwordx4 v[90:93], v184, s[26:27] nt
	global_load_dwordx4 v[110:113], v184, s[28:29] nt
	s_waitcnt vmcnt(28)
	v_cvt_pk_bf16_f32 v244, v106, v107
	v_cvt_pk_bf16_f32 v245, v108, v109
	ds_write_b64 v212, v[244:245]
	v_cvt_pk_bf16_f32 v180, v118, v119
	v_cvt_pk_bf16_f32 v181, v120, v121
	ds_write_b64 v213, v[180:181] offset:8192
	v_cvt_pk_bf16_f32 v244, v138, v139
	v_cvt_pk_bf16_f32 v245, v140, v141
	ds_write_b64 v214, v[244:245]
	v_cvt_pk_bf16_f32 v180, v142, v143
	v_cvt_pk_bf16_f32 v181, v144, v145
	ds_write_b64 v215, v[180:181] offset:8192
	s_add_u32 s30, s95, s94
	s_add_u32 s26, s72, s30
	s_addc_u32 s27, s73, 0
	s_add_u32 s28, s74, s30
	s_addc_u32 s29, s75, 0
	s_add_u32 s94, s94, 0x2000
	s_and_b32 s94, s94, 0x3ffff
	global_load_dwordx4 v[106:109], v184, s[26:27] offset:-4096 nt
	global_load_dwordx4 v[118:121], v184, s[28:29] offset:-4096 nt
	global_load_dwordx4 v[138:141], v184, s[26:27] nt
	global_load_dwordx4 v[142:145], v184, s[28:29] nt
	s_waitcnt vmcnt(28)
	v_cvt_pk_bf16_f32 v244, v146, v147
	v_cvt_pk_bf16_f32 v245, v148, v149
	ds_write_b64 v216, v[244:245]
	v_cvt_pk_bf16_f32 v180, v150, v151
	v_cvt_pk_bf16_f32 v181, v152, v153
	ds_write_b64 v217, v[180:181] offset:8192
	v_cvt_pk_bf16_f32 v244, v154, v155
	v_cvt_pk_bf16_f32 v245, v156, v157
	ds_write_b64 v218, v[244:245]
	v_cvt_pk_bf16_f32 v180, v158, v159
	v_cvt_pk_bf16_f32 v181, v160, v161
	ds_write_b64 v219, v[180:181] offset:8192
	s_add_u32 s30, s95, s94
	s_add_u32 s26, s72, s30
	s_addc_u32 s27, s73, 0
	s_add_u32 s28, s74, s30
	s_addc_u32 s29, s75, 0
	s_add_u32 s94, s94, 0x2000
	s_and_b32 s94, s94, 0x3ffff
	global_load_dwordx4 v[146:149], v184, s[26:27] offset:-4096 nt
	global_load_dwordx4 v[150:153], v184, s[28:29] offset:-4096 nt
	global_load_dwordx4 v[154:157], v184, s[26:27] nt
	global_load_dwordx4 v[158:161], v184, s[28:29] nt
	s_waitcnt vmcnt(28)
	v_cvt_pk_bf16_f32 v244, v162, v163
	v_cvt_pk_bf16_f32 v245, v164, v165
	ds_write_b64 v220, v[244:245]
	v_cvt_pk_bf16_f32 v180, v166, v167
	v_cvt_pk_bf16_f32 v181, v168, v169
	ds_write_b64 v221, v[180:181] offset:8192
	v_cvt_pk_bf16_f32 v244, v170, v171
	v_cvt_pk_bf16_f32 v245, v172, v173
	ds_write_b64 v227, v[244:245]
	v_cvt_pk_bf16_f32 v180, v174, v175
	v_cvt_pk_bf16_f32 v181, v176, v177
	ds_write_b64 v228, v[180:181] offset:8192
	s_add_u32 s30, s95, s94
	s_add_u32 s26, s72, s30
	s_addc_u32 s27, s73, 0
	s_add_u32 s28, s74, s30
	s_addc_u32 s29, s75, 0
	s_add_u32 s94, s94, 0x2000
	s_and_b32 s94, s94, 0x3ffff
	global_load_dwordx4 v[162:165], v184, s[26:27] offset:-4096 nt
	global_load_dwordx4 v[166:169], v184, s[28:29] offset:-4096 nt
	global_load_dwordx4 v[170:173], v184, s[26:27] nt
	global_load_dwordx4 v[174:177], v184, s[28:29] nt
	s_branch .LBB0_543
.Lsp_last_a:
	s_waitcnt vmcnt(29)
	v_cvt_pk_bf16_f32 v244, v26, v27
	v_cvt_pk_bf16_f32 v245, v28, v29
	ds_write_b64 v196, v[244:245]
	s_waitcnt vmcnt(27)
	v_cvt_pk_bf16_f32 v244, v34, v35
	v_cvt_pk_bf16_f32 v245, v36, v37
	ds_write_b64 v197, v[244:245] offset:8192
	v_cvt_pk_bf16_f32 v244, v30, v31
	v_cvt_pk_bf16_f32 v245, v32, v33
	ds_write_b64 v198, v[244:245]
	s_waitcnt vmcnt(26)
	v_cvt_pk_bf16_f32 v244, v38, v39
	v_cvt_pk_bf16_f32 v245, v40, v41
	ds_write_b64 v199, v[244:245] offset:8192
	s_waitcnt vmcnt(25)
	v_cvt_pk_bf16_f32 v244, v42, v43
	v_cvt_pk_bf16_f32 v245, v44, v45
	ds_write_b64 v200, v[244:245]
	s_waitcnt vmcnt(23)
	v_cvt_pk_bf16_f32 v244, v50, v51
	v_cvt_pk_bf16_f32 v245, v52, v53
	ds_write_b64 v201, v[244:245] offset:8192
	v_cvt_pk_bf16_f32 v244, v46, v47
	v_cvt_pk_bf16_f32 v245, v48, v49
	ds_write_b64 v202, v[244:245]
	s_waitcnt vmcnt(22)
	v_cvt_pk_bf16_f32 v244, v54, v55
	v_cvt_pk_bf16_f32 v245, v56, v57
	ds_write_b64 v203, v[244:245] offset:8192
	s_waitcnt vmcnt(21)
	v_cvt_pk_bf16_f32 v244, v58, v59
	v_cvt_pk_bf16_f32 v245, v60, v61
	ds_write_b64 v204, v[244:245]
	s_waitcnt vmcnt(19)
	v_cvt_pk_bf16_f32 v244, v66, v67
	v_cvt_pk_bf16_f32 v245, v68, v69
	ds_write_b64 v205, v[244:245] offset:8192
	v_cvt_pk_bf16_f32 v244, v62, v63
	v_cvt_pk_bf16_f32 v245, v64, v65
	ds_write_b64 v206, v[244:245]
	s_waitcnt vmcnt(18)
	v_cvt_pk_bf16_f32 v244, v70, v71
	v_cvt_pk_bf16_f32 v245, v72, v73
	ds_write_b64 v207, v[244:245] offset:8192
	s_waitcnt vmcnt(17)
	v_cvt_pk_bf16_f32 v244, v74, v75
	v_cvt_pk_bf16_f32 v245, v76, v77
	ds_write_b64 v208, v[244:245]
	s_waitcnt vmcnt(15)
	v_cvt_pk_bf16_f32 v244, v82, v83
	v_cvt_pk_bf16_f32 v245, v84, v85
	v_cvt_pk_bf16_f32 v180, v18, v19
	v_cvt_pk_bf16_f32 v181, v20, v21
	ds_write_b64 v209, v[244:245] offset:8192
	v_cvt_pk_bf16_f32 v244, v78, v79
	v_cvt_pk_bf16_f32 v245, v80, v81
	v_cvt_pk_bf16_f32 v242, v22, v23
	v_cvt_pk_bf16_f32 v243, v24, v25
	ds_write2st64_b64 v194, v[180:181], v[244:245] offset1:8
	s_waitcnt vmcnt(14)
	v_cvt_pk_bf16_f32 v180, v86, v87
	v_cvt_pk_bf16_f32 v181, v88, v89
	ds_write2st64_b64 v195, v[242:243], v[180:181] offset0:16 offset1:24
	s_waitcnt vmcnt(13)
	v_cvt_pk_bf16_f32 v180, v90, v91
	v_cvt_pk_bf16_f32 v181, v92, v93
	ds_write_b64 v210, v[180:181]
	s_waitcnt vmcnt(11)
	v_cvt_pk_bf16_f32 v180, v110, v111
	v_cvt_pk_bf16_f32 v181, v112, v113
	ds_write_b64 v211, v[180:181] offset:8192
	v_cvt_pk_bf16_f32 v180, v106, v107
	v_cvt_pk_bf16_f32 v181, v108, v109
	ds_write_b64 v212, v[180:181]
	s_waitcnt vmcnt(10)
	v_cvt_pk_bf16_f32 v180, v118, v119
	v_cvt_pk_bf16_f32 v181, v120, v121
	ds_write_b64 v213, v[180:181] offset:8192
	s_waitcnt vmcnt(9)
	v_cvt_pk_bf16_f32 v180, v138, v139
	v_cvt_pk_bf16_f32 v181, v140, v141
	ds_write_b64 v214, v[180:181]
	s_waitcnt vmcnt(7)
	v_cvt_pk_bf16_f32 v180, v142, v143
	v_cvt_pk_bf16_f32 v181, v144, v145
	ds_write_b64 v215, v[180:181] offset:8192
	v_cvt_pk_bf16_f32 v180, v146, v147
	v_cvt_pk_bf16_f32 v181, v148, v149
	ds_write_b64 v216, v[180:181]
	s_waitcnt vmcnt(6)
	v_cvt_pk_bf16_f32 v180, v150, v151
	v_cvt_pk_bf16_f32 v181, v152, v153
	ds_write_b64 v217, v[180:181] offset:8192
	s_waitcnt vmcnt(5)
	v_cvt_pk_bf16_f32 v180, v154, v155
	v_cvt_pk_bf16_f32 v181, v156, v157
	ds_write_b64 v218, v[180:181]
	s_waitcnt vmcnt(3)
	v_cvt_pk_bf16_f32 v180, v158, v159
	v_cvt_pk_bf16_f32 v181, v160, v161
	ds_write_b64 v219, v[180:181] offset:8192
	v_cvt_pk_bf16_f32 v180, v162, v163
	v_cvt_pk_bf16_f32 v181, v164, v165
	ds_write_b64 v220, v[180:181]
	s_waitcnt vmcnt(2)
	v_cvt_pk_bf16_f32 v180, v166, v167
	v_cvt_pk_bf16_f32 v181, v168, v169
	ds_write_b64 v221, v[180:181] offset:8192
	s_waitcnt vmcnt(1)
	v_cvt_pk_bf16_f32 v180, v170, v171
	v_cvt_pk_bf16_f32 v181, v172, v173
	s_add_i32 s25, s24, 1
	ds_write_b64 v227, v[180:181]
	s_waitcnt vmcnt(0)
	v_cvt_pk_bf16_f32 v180, v174, v175
	v_cvt_pk_bf16_f32 v181, v176, v177
	s_cmp_lg_u32 s24, 15
	ds_write_b64 v228, v[180:181] offset:8192
	s_cbranch_scc0 .LBB0_541
.LBB0_541:
	s_and_b32 s26, s24, 3
	s_cmp_eq_u32 s26, 0
	s_cselect_b64 s[26:27], -1, 0
	s_cmp_lt_u32 s24, 12
	s_cselect_b64 s[28:29], -1, 0
	s_and_b64 s[26:27], s[26:27], s[28:29]
	s_andn2_b64 vcc, exec, s[26:27]
	s_cbranch_vccnz .LBB0_543
.LBB0_543:
	ds_read_b128 v[242:245], v229
	ds_read_b128 v[246:249], v230
	s_add_i32 s22, s22, 32
	s_cmp_eq_u32 s25, 16
	s_waitcnt lgkmcnt(1)
	v_mfma_f32_16x16x32_bf16 v[242:245], v[242:245], v[2:5], 0
	ds_read_b128 v[250:253], v230 offset:4096
	s_waitcnt lgkmcnt(1)
	v_mfma_f32_16x16x32_bf16 v[242:245], v[246:249], v[10:13], v[242:245]
	ds_read_b128 v[246:249], v231
	s_waitcnt lgkmcnt(0)
	v_mfma_f32_16x16x32_bf16 v[242:245], v[246:249], v[6:9], v[242:245]
	ds_read_b128 v[246:249], v232
	s_waitcnt lgkmcnt(0)
	v_mfma_f32_16x16x32_bf16 v[242:245], v[246:249], v[14:17], v[242:245]
	ds_read_b128 v[246:249], v229 offset:4096
	s_nop 6
	v_max_f32_e32 v179, v243, v243
	v_max_f32_e32 v180, v242, v242
	v_max_f32_e32 v179, v180, v179
	s_waitcnt lgkmcnt(0)
	v_mfma_f32_16x16x32_bf16 v[246:249], v[246:249], v[2:5], 0
	v_max_f32_e32 v180, v245, v245
	v_max_f32_e32 v181, v244, v244
	v_max_f32_e32 v180, v181, v180
	v_mfma_f32_16x16x32_bf16 v[246:249], v[250:253], v[10:13], v[246:249]
	ds_read_b128 v[250:253], v231 offset:4096
	s_waitcnt lgkmcnt(0)
	v_mfma_f32_16x16x32_bf16 v[246:249], v[250:253], v[6:9], v[246:249]
	ds_read_b128 v[250:253], v232 offset:4096
	s_waitcnt lgkmcnt(0)
	v_mfma_f32_16x16x32_bf16 v[246:249], v[250:253], v[14:17], v[246:249]
	s_nop 7
	v_max_f32_e32 v181, v249, v249
	v_max_f32_e32 v186, v248, v248
	v_max_f32_e32 v181, v186, v181
	v_max3_f32 v181, v246, v247, v181
	v_max3_f32 v179, v179, v180, v181
	v_mov_b32_e32 v180, v179
	s_nop 1
	v_permlane16_swap_b32_e32 v179, v180
	v_max_f32_e32 v180, v180, v180
	v_max_f32_e32 v179, v179, v179
	v_max_f32_e32 v179, v179, v180
	v_mov_b32_e32 v180, v179
	s_nop 1
	v_permlane32_swap_b32_e32 v179, v180
	v_max3_f32 v241, v178, v179, v180
	v_sub_f32_e32 v178, v178, v241
	v_exp_f32_e32 v186, v178
	v_sub_f32_e32 v181, v245, v241
	v_sub_f32_e32 v180, v244, v241
	v_sub_f32_e32 v179, v243, v241
	v_sub_f32_e32 v178, v242, v241
	v_sub_f32_e32 v242, v249, v241
	v_sub_f32_e32 v243, v248, v241
	v_sub_f32_e32 v245, v247, v241
	v_sub_f32_e32 v244, v246, v241
	v_exp_f32_e32 v178, v178
	v_exp_f32_e32 v179, v179
	v_exp_f32_e32 v180, v180
	v_exp_f32_e32 v181, v181
	v_exp_f32_e32 v244, v244
	v_exp_f32_e32 v245, v245
	v_exp_f32_e32 v246, v243
	v_exp_f32_e32 v247, v242
	v_pk_mul_f32 v[136:137], v[136:137], v[186:187] op_sel_hi:[1,0]
	v_pk_add_f32 v[248:249], v[178:179], v[244:245]
	v_cvt_pk_bf16_f32 v178, v178, v179
	v_pk_add_f32 v[242:243], v[180:181], v[246:247]
	v_cvt_pk_bf16_f32 v179, v180, v181
	v_cvt_pk_bf16_f32 v180, v244, v245
	v_cvt_pk_bf16_f32 v181, v246, v247
	ds_read_b64_tr_b16 v[244:245], v233 offset:8192
	ds_read_b64_tr_b16 v[246:247], v233 offset:12288
	v_pk_mul_f32 v[134:135], v[134:135], v[186:187] op_sel_hi:[1,0]
	v_pk_mul_f32 v[132:133], v[132:133], v[186:187] op_sel_hi:[1,0]
	v_pk_mul_f32 v[130:131], v[130:131], v[186:187] op_sel_hi:[1,0]
	s_waitcnt lgkmcnt(0)
	v_mfma_f32_16x16x32_bf16 v[134:137], v[244:247], v[178:181], v[134:137]
	ds_read_b64_tr_b16 v[244:245], v234 offset:8192
	ds_read_b64_tr_b16 v[246:247], v234 offset:12288
	v_pk_mul_f32 v[128:129], v[128:129], v[186:187] op_sel_hi:[1,0]
	v_pk_mul_f32 v[126:127], v[126:127], v[186:187] op_sel_hi:[1,0]
	s_waitcnt lgkmcnt(0)
	v_mfma_f32_16x16x32_bf16 v[130:133], v[244:247], v[178:181], v[130:133]
	ds_read_b64_tr_b16 v[244:245], v235 offset:8192
	ds_read_b64_tr_b16 v[246:247], v235 offset:12288
	v_pk_mul_f32 v[124:125], v[124:125], v[186:187] op_sel_hi:[1,0]
	v_pk_mul_f32 v[122:123], v[122:123], v[186:187] op_sel_hi:[1,0]
	s_waitcnt lgkmcnt(0)
	v_mfma_f32_16x16x32_bf16 v[126:129], v[244:247], v[178:181], v[126:129]
	ds_read_b64_tr_b16 v[244:245], v236 offset:8192
	ds_read_b64_tr_b16 v[246:247], v236 offset:12288
	v_pk_mul_f32 v[116:117], v[116:117], v[186:187] op_sel_hi:[1,0]
	v_pk_mul_f32 v[114:115], v[114:115], v[186:187] op_sel_hi:[1,0]
	s_waitcnt lgkmcnt(0)
	v_mfma_f32_16x16x32_bf16 v[122:125], v[244:247], v[178:181], v[122:125]
	ds_read_b64_tr_b16 v[244:245], v237 offset:8192
	ds_read_b64_tr_b16 v[246:247], v237 offset:12288
	v_pk_mul_f32 v[104:105], v[104:105], v[186:187] op_sel_hi:[1,0]
	v_pk_mul_f32 v[102:103], v[102:103], v[186:187] op_sel_hi:[1,0]
	s_waitcnt lgkmcnt(0)
	v_mfma_f32_16x16x32_bf16 v[114:117], v[244:247], v[178:181], v[114:117]
	ds_read_b64_tr_b16 v[244:245], v238 offset:8192
	ds_read_b64_tr_b16 v[246:247], v238 offset:12288
	v_pk_mul_f32 v[100:101], v[100:101], v[186:187] op_sel_hi:[1,0]
	v_pk_mul_f32 v[98:99], v[98:99], v[186:187] op_sel_hi:[1,0]
	s_waitcnt lgkmcnt(0)
	v_mfma_f32_16x16x32_bf16 v[102:105], v[244:247], v[178:181], v[102:105]
	ds_read_b64_tr_b16 v[244:245], v239 offset:8192
	ds_read_b64_tr_b16 v[246:247], v239 offset:12288
	v_pk_mul_f32 v[96:97], v[96:97], v[186:187] op_sel_hi:[1,0]
	v_pk_mul_f32 v[94:95], v[94:95], v[186:187] op_sel_hi:[1,0]
	s_waitcnt lgkmcnt(0)
	v_mfma_f32_16x16x32_bf16 v[98:101], v[244:247], v[178:181], v[98:101]
	ds_read_b64_tr_b16 v[244:245], v240 offset:8192
	ds_read_b64_tr_b16 v[246:247], v240 offset:12288
	v_pk_mov_b32 v[250:251], v[248:249], v[242:243] op_sel:[1,0]
	v_mov_b32_e32 v249, v243
	s_waitcnt lgkmcnt(0)
	v_mfma_f32_16x16x32_bf16 v[94:97], v[244:247], v[178:181], v[94:97]
	v_add_f32_e64 v242, v250, v248
	v_add_f32_e64 v243, v251, v249
	v_add_f32_e32 v242, v242, v243
	v_fmac_f32_e32 v242, v193, v186
	s_cbranch_scc1 .LBB0_545
	v_mov_b32_e32 v193, v242
	v_mov_b32_e32 v178, v241
	s_mov_b32 s24, s25
	s_branch .LBB0_539

.LBB0_595:
	s_or_b64 exec, exec, s[0:1]
	s_ashr_i32 s7, s20, 3
	s_ashr_i32 s4, s23, 8
	s_and_b32 s94, s20, 31
	s_lshl_b32 s94, s94, 13
	s_lshl_b32 s0, s7, 6
	s_ashr_i32 s1, s0, 31
	s_lshl_b32 s26, s4, 2
	s_and_b32 s6, s20, 7
	s_ashr_i32 s27, s26, 31
	s_lshl_b64 s[0:1], s[0:1], 2
	s_add_u32 s0, s76, s0
	s_addc_u32 s1, s77, s1
	s_lshl_b32 s23, s6, 5
	s_add_u32 s23, s0, s23
	s_addc_u32 s28, s1, 0
	s_lshl_b32 s0, s22, 14
	s_add_i32 s25, s0, 0
	s_lshl_b64 s[0:1], s[26:27], 2
	s_add_u32 s0, s23, s0
	s_addc_u32 s1, s28, s1
	s_load_dwordx2 s[98:99], s[0:1], 0x0
	s_load_dwordx2 s[100:101], s[0:1], 0x8
	global_load_dword v18, v183, s[0:1]
	v_bfe_u32 v19, v20, 4, 2
	v_and_b32_e32 v188, 63, v20
	v_lshlrev_b32_e32 v103, 3, v20
	v_lshrrev_b32_e32 v21, 2, v185
	v_lshlrev_b32_e32 v187, 2, v19
	s_waitcnt vmcnt(39)
	v_xor_b32_e32 v22, v19, v185
	v_bitop3_b32 v23, v19, v185, 4 bitop3:0x36
	v_bitop3_b32 v24, v19, v185, 8 bitop3:0x36
	v_bitop3_b32 v25, v19, v185, 12 bitop3:0x36
	v_and_b32_e32 v105, 24, v103
	v_lshrrev_b32_e32 v182, 5, v188
	v_or_b32_e32 v19, v187, v21
	v_lshl_or_b32 v122, v19, 8, v105
	v_lshlrev_b32_e32 v19, 5, v19
	s_movk_i32 s23, 0xe0
	v_and_b32_e32 v123, 0xe0, v19
	v_bitop3_b32 v124, v19, s23, v122 bitop3:0x26
	v_and_b32_e32 v102, 31, v20
	v_bfe_u32 v104, v20, 2, 3
	v_lshlrev_b32_e32 v20, 8, v185
	v_lshl_or_b32 v114, v22, 4, v20
	v_lshl_or_b32 v115, v23, 4, v20
	v_lshl_or_b32 v116, v24, 4, v20
	v_lshl_or_b32 v117, v25, 4, v20
	v_or_b32_e32 v178, 10, v182
	v_lshl_add_u32 v181, v178, 8, s25
	v_lshlrev_b32_e32 v184, 4, v178
	v_bitop3_b32 v178, v178, v104, 3 bitop3:0x6c
	v_lshl_add_u32 v202, v178, 5, v181
	v_or_b32_e32 v178, 12, v182
	v_bitop3_b32 v186, v184, v103, s19 bitop3:0x78
	v_lshl_add_u32 v203, v178, 8, s25
	v_lshlrev_b32_e32 v184, 4, v178
	v_bitop3_b32 v178, v178, v104, 5 bitop3:0x6c
	v_lshl_add_u32 v205, v178, 5, v203
	v_or_b32_e32 v178, 14, v182
	v_or_b32_e32 v131, 4, v182
	v_or_b32_e32 v134, 6, v182
	v_or_b32_e32 v137, 8, v182
	v_bitop3_b32 v204, v184, v103, s19 bitop3:0x78
	v_lshl_add_u32 v206, v178, 8, s25
	v_lshlrev_b32_e32 v184, 4, v178
	v_bitop3_b32 v178, v178, v104, 7 bitop3:0x6c
	v_lshl_add_u32 v132, v131, 8, s25
	v_lshlrev_b32_e32 v131, 4, v131
	v_lshl_add_u32 v135, v134, 8, s25
	v_lshlrev_b32_e32 v134, 4, v134
	v_lshl_add_u32 v179, v137, 8, s25
	v_lshlrev_b32_e32 v137, 4, v137
	v_lshl_add_u32 v207, v178, 5, v206
	v_or_b32_e32 v178, 18, v182
	v_bitop3_b32 v131, v131, v103, s19 bitop3:0x78
	v_bitop3_b32 v134, v134, v103, s19 bitop3:0x78
	v_bitop3_b32 v137, v137, v103, s19 bitop3:0x78
	v_lshl_add_u32 v208, v178, 8, s25
	s_movk_i32 s23, 0x60
	v_bitop3_b32 v127, v123, s23, v122 bitop3:0x36
	s_movk_i32 s23, 0x80
	v_bitop3_b32 v128, v123, s23, v122 bitop3:0x36
	s_movk_i32 s23, 0xa0
	v_bitop3_b32 v129, v123, s23, v122 bitop3:0x36
	s_movk_i32 s23, 0xc0
	v_bitop3_b32 v133, v182, v104, 4 bitop3:0x36
	v_bitop3_b32 v136, v182, v104, 6 bitop3:0x36
	v_bitop3_b32 v125, v123, 32, v122 bitop3:0x36
	v_bitop3_b32 v126, v123, 64, v122 bitop3:0x36
	v_bitop3_b32 v130, v123, s23, v122 bitop3:0x36
	s_lshl_b32 s23, s21, 7
	v_lshl_add_u32 v133, v133, 5, v132
	v_lshl_add_u32 v136, v136, 5, v135
	v_add_u32_e32 v123, s25, v123
	s_mov_b32 s22, 32
	v_add_u32_e32 v194, v132, v131
	v_add_u32_e32 v195, v133, v105
	v_add_u32_e32 v197, v135, v134
	v_add_u32_e32 v198, v136, v105
	v_add_u32_e32 v199, v179, v137
	v_add_u32_e32 v201, v181, v186
	v_add_u32_e32 v202, v202, v105
	s_waitcnt vmcnt(0)
	v_readfirstlane_b32 s26, v18
	s_ashr_i32 s27, s26, 31
	s_lshl_b64 s[26:27], s[26:27], 9
	v_lshl_or_b32 v18, v182, 2, s26
	v_mov_b32_e32 v19, s27
	v_or_b32_e32 v18, s21, v18
	v_lshlrev_b64 v[18:19], 9, v[18:19]
	v_lshl_or_b32 v18, v102, 4, v18
	v_lshl_add_u64 v[94:95], s[72:73], 0, v[18:19]
	v_add_co_u32_e32 v30, vcc, s11, v94
	v_lshl_add_u64 v[96:97], s[74:75], 0, v[18:19]
	s_nop 0
	v_addc_co_u32_e32 v31, vcc, 0, v95, vcc
	v_add_co_u32_e32 v38, vcc, s11, v96
	v_addc_co_u32_e32 v39, vcc, 0, v97, vcc
	v_add_co_u32_e32 v46, vcc, s10, v94
	s_movk_i32 s26, 0x50
	s_nop 0
	v_addc_co_u32_e32 v47, vcc, 0, v95, vcc
	v_add_co_u32_e32 v54, vcc, s10, v96
	v_add_u32_e32 v203, v203, v204
	s_nop 0
	v_addc_co_u32_e32 v55, vcc, 0, v97, vcc
	v_add_co_u32_e32 v62, vcc, s12, v94
	v_add_u32_e32 v204, v205, v105
	s_nop 0
	v_addc_co_u32_e32 v63, vcc, 0, v95, vcc
	v_add_co_u32_e32 v70, vcc, s12, v96
	v_add_u32_e32 v231, s25, v125
	s_nop 0
	v_addc_co_u32_e32 v71, vcc, 0, v97, vcc
	v_add_co_u32_e32 v78, vcc, s13, v94
	s_nop 0
	s_nop 0
	s_nop 0
	s_nop 0
	s_nop 0
	s_nop 0
	s_nop 0
	s_nop 0
	s_nop 0
	s_nop 0
	s_nop 0
	v_addc_co_u32_e32 v79, vcc, 0, v95, vcc
	v_add_co_u32_e32 v86, vcc, s13, v96
	v_add_u32_e32 v232, s25, v126
	s_nop 0
	v_addc_co_u32_e32 v87, vcc, 0, v97, vcc
	v_add_co_u32_e32 v98, vcc, s14, v94
	s_nop 0
	s_nop 0
	s_nop 0
	v_addc_co_u32_e32 v99, vcc, 0, v95, vcc
	v_add_co_u32_e32 v100, vcc, s14, v96
	v_add_u32_e32 v233, s25, v127
	s_nop 0
	v_addc_co_u32_e32 v101, vcc, 0, v97, vcc
	v_add_co_u32_e32 v98, vcc, s15, v94
	v_add_u32_e32 v234, s25, v128
	s_nop 0
	v_addc_co_u32_e32 v99, vcc, 0, v95, vcc
	v_add_co_u32_e32 v100, vcc, s15, v96
	v_add_u32_e32 v235, s25, v129
	s_nop 0
	v_addc_co_u32_e32 v101, vcc, 0, v97, vcc
	v_add_co_u32_e32 v98, vcc, s17, v94
	v_add_u32_e32 v236, s25, v130
	s_nop 0
	v_addc_co_u32_e32 v99, vcc, 0, v95, vcc
	v_add_co_u32_e32 v100, vcc, s17, v96
	v_add_u32_e32 v237, s25, v124
	s_nop 0
	v_addc_co_u32_e32 v101, vcc, 0, v97, vcc
	v_add_co_u32_e32 v94, vcc, s18, v94
	v_addc_co_u32_e32 v95, vcc, 0, v95, vcc
	v_add_co_u32_e32 v94, vcc, s18, v96
	v_or_b32_e32 v99, 2, v182
	s_nop 0
	v_addc_co_u32_e32 v95, vcc, 0, v97, vcc
	v_lshlrev_b32_e32 v96, 4, v182
	v_lshl_add_u32 v100, v99, 8, s25
	v_lshlrev_b32_e32 v99, 4, v99
	v_and_b32_e32 v94, 0xf8, v103
	v_bitop3_b32 v96, v103, v96, s19 bitop3:0x6c
	v_bitop3_b32 v99, v99, v103, s19 bitop3:0x78
	v_bitop3_b32 v103, v184, v103, s19 bitop3:0x78
	v_lshlrev_b32_e32 v184, 4, v178
	v_bitop3_b32 v178, v178, v104, 3 bitop3:0x6c
	v_lshl_add_u32 v210, v178, 5, v208
	v_or_b32_e32 v178, 20, v182
	v_bitop3_b32 v209, v184, v94, 48 bitop3:0x6c
	v_lshl_add_u32 v211, v178, 8, s25
	v_lshlrev_b32_e32 v184, 4, v178
	v_bitop3_b32 v178, v178, v104, 5 bitop3:0x6c
	v_lshl_add_u32 v213, v178, 5, v211
	v_or_b32_e32 v178, 22, v182
	v_bitop3_b32 v212, v184, v94, s26 bitop3:0x6c
	v_lshl_add_u32 v214, v178, 8, s25
	v_lshlrev_b32_e32 v184, 4, v178
	v_bitop3_b32 v178, v178, v104, 7 bitop3:0x6c
	s_movk_i32 s26, 0x70
	v_lshl_add_u32 v216, v178, 5, v214
	v_or_b32_e32 v178, 24, v182
	v_bitop3_b32 v215, v184, v94, s26 bitop3:0x6c
	v_lshl_add_u32 v217, v178, 8, s25
	v_lshlrev_b32_e32 v178, 4, v178
	s_movk_i32 s26, 0x90
	v_bitop3_b32 v218, v178, v94, s26 bitop3:0x6c
	v_or_b32_e32 v178, 26, v182
	v_lshl_add_u32 v219, v178, 8, s25
	v_lshlrev_b32_e32 v184, 4, v178
	v_bitop3_b32 v178, v178, v104, 3 bitop3:0x6c
	s_movk_i32 s26, 0xb0
	v_lshl_add_u32 v221, v178, 5, v219
	v_or_b32_e32 v178, 28, v182
	v_bitop3_b32 v220, v184, v94, s26 bitop3:0x6c
	v_lshl_add_u32 v227, v178, 8, s25
	v_lshlrev_b32_e32 v184, 4, v178
	v_bitop3_b32 v178, v178, v104, 5 bitop3:0x6c
	v_xor_b32_e32 v97, v182, v104
	s_movk_i32 s26, 0xd0
	v_lshl_add_u32 v229, v178, 5, v227
	v_or_b32_e32 v178, 30, v182
	v_lshl_add_u32 v95, v182, 8, s25
	v_lshlrev_b32_e32 v97, 5, v97
	v_bitop3_b32 v101, v182, v104, 2 bitop3:0x36
	v_bitop3_b32 v228, v184, v94, s26 bitop3:0x6c
	v_lshl_add_u32 v230, v178, 8, s25
	v_lshlrev_b32_e32 v184, 4, v178
	s_movk_i32 s26, 0xf0
	v_bitop3_b32 v104, v178, v104, 7 bitop3:0x6c
	v_add_u32_e32 v98, v95, v97
	v_lshl_add_u32 v101, v101, 5, v100
	v_add_u32_e32 v180, v179, v97
	v_add_u32_e32 v97, v217, v97
	v_bitop3_b32 v94, v184, v94, s26 bitop3:0x6c
	v_lshl_add_u32 v104, v104, 5, v230
	v_lshl_or_b32 v184, v102, 2, s23
	v_lshlrev_b32_e32 v184, 2, v184
	v_lshl_or_b32 v184, v182, 11, v184
	v_mov_b32_e32 v178, 0xf149f2ca
	v_add_u32_e32 v190, v95, v96
	v_add_u32_e32 v191, v98, v105
	v_add_u32_e32 v192, v100, v99
	v_add_u32_e32 v193, v101, v105
	v_add_u32_e32 v200, v180, v105
	v_add_u32_e32 v205, v206, v103
	v_add_u32_e32 v206, v207, v105
	v_add_u32_e32 v207, v208, v209
	v_add_u32_e32 v208, v210, v105
	v_add_u32_e32 v209, v211, v212
	v_add_u32_e32 v210, v213, v105
	v_add_u32_e32 v211, v214, v215
	v_add_u32_e32 v212, v216, v105
	v_add_u32_e32 v213, v217, v218
	v_add_u32_e32 v214, v97, v105
	v_add_u32_e32 v215, v219, v220
	v_add_u32_e32 v216, v221, v105
	v_add_u32_e32 v217, v227, v228
	v_add_u32_e32 v218, v229, v105
	v_add_u32_e32 v219, v230, v94
	v_add_u32_e32 v220, v104, v105
	s_lshl_b32 s23, s23, 2
	v_add_u32_e32 v221, s25, v114
	v_add_u32_e32 v227, s25, v115
	v_add_u32_e32 v228, s25, v116
	v_add_u32_e32 v229, s25, v117
	v_add_u32_e32 v230, v123, v122
	v_mov_b32_e32 v94, 0
	v_mov_b32_e32 v95, v189
	v_mov_b32_e32 v96, v189
	v_mov_b32_e32 v97, v189
	v_mov_b32_e32 v98, 0
	v_mov_b32_e32 v99, v189
	v_mov_b32_e32 v100, v189
	v_mov_b32_e32 v101, v189
	v_mov_b32_e32 v102, 0
	v_mov_b32_e32 v103, v189
	v_mov_b32_e32 v104, v189
	v_mov_b32_e32 v105, v189
	v_mov_b32_e32 v114, 0
	v_mov_b32_e32 v115, v189
	v_mov_b32_e32 v116, v189
	v_mov_b32_e32 v117, v189
	v_mov_b32_e32 v122, 0
	v_mov_b32_e32 v123, v189
	v_mov_b32_e32 v124, v189
	v_mov_b32_e32 v125, v189
	v_mov_b32_e32 v126, 0
	v_mov_b32_e32 v127, v189
	v_mov_b32_e32 v128, v189
	v_mov_b32_e32 v129, v189
	v_mov_b32_e32 v130, 0
	v_mov_b32_e32 v131, v189
	v_mov_b32_e32 v132, v189
	v_mov_b32_e32 v133, v189
	v_mov_b32_e32 v134, 0
	v_mov_b32_e32 v135, v189
	v_mov_b32_e32 v136, v189
	v_mov_b32_e32 v137, v189
	s_waitcnt lgkmcnt(0)
	s_lshl_b32 s95, s98, 18
	s_add_u32 s95, s95, 0x1000
	s_add_u32 s30, s95, s94
	s_add_u32 s26, s72, s30
	s_addc_u32 s27, s73, 0
	s_add_u32 s28, s74, s30
	s_addc_u32 s29, s75, 0
	s_add_u32 s94, s94, 0x2000
	s_and_b32 s94, s94, 0x3ffff
	global_load_dwordx4 v[18:21], v184, s[26:27] offset:-4096 nt
	global_load_dwordx4 v[22:25], v184, s[28:29] offset:-4096 nt
	global_load_dwordx4 v[26:29], v184, s[26:27] nt
	global_load_dwordx4 v[34:37], v184, s[28:29] nt
	s_add_u32 s30, s95, s94
	s_add_u32 s26, s72, s30
	s_addc_u32 s27, s73, 0
	s_add_u32 s28, s74, s30
	s_addc_u32 s29, s75, 0
	s_add_u32 s94, s94, 0x2000
	s_and_b32 s94, s94, 0x3ffff
	global_load_dwordx4 v[30:33], v184, s[26:27] offset:-4096 nt
	global_load_dwordx4 v[38:41], v184, s[28:29] offset:-4096 nt
	global_load_dwordx4 v[42:45], v184, s[26:27] nt
	global_load_dwordx4 v[50:53], v184, s[28:29] nt
	s_add_u32 s30, s95, s94
	s_add_u32 s26, s72, s30
	s_addc_u32 s27, s73, 0
	s_add_u32 s28, s74, s30
	s_addc_u32 s29, s75, 0
	s_add_u32 s94, s94, 0x2000
	s_and_b32 s94, s94, 0x3ffff
	global_load_dwordx4 v[46:49], v184, s[26:27] offset:-4096 nt
	global_load_dwordx4 v[54:57], v184, s[28:29] offset:-4096 nt
	global_load_dwordx4 v[58:61], v184, s[26:27] nt
	global_load_dwordx4 v[66:69], v184, s[28:29] nt
	s_add_u32 s30, s95, s94
	s_add_u32 s26, s72, s30
	s_addc_u32 s27, s73, 0
	s_add_u32 s28, s74, s30
	s_addc_u32 s29, s75, 0
	s_add_u32 s94, s94, 0x2000
	s_and_b32 s94, s94, 0x3ffff
	global_load_dwordx4 v[62:65], v184, s[26:27] offset:-4096 nt
	global_load_dwordx4 v[70:73], v184, s[28:29] offset:-4096 nt
	global_load_dwordx4 v[74:77], v184, s[26:27] nt
	global_load_dwordx4 v[82:85], v184, s[28:29] nt
	s_add_u32 s30, s95, s94
	s_add_u32 s26, s72, s30
	s_addc_u32 s27, s73, 0
	s_add_u32 s28, s74, s30
	s_addc_u32 s29, s75, 0
	s_add_u32 s94, s94, 0x2000
	s_and_b32 s94, s94, 0x3ffff
	global_load_dwordx4 v[78:81], v184, s[26:27] offset:-4096 nt
	global_load_dwordx4 v[86:89], v184, s[28:29] offset:-4096 nt
	global_load_dwordx4 v[90:93], v184, s[26:27] nt
	global_load_dwordx4 v[110:113], v184, s[28:29] nt
	s_add_u32 s30, s95, s94
	s_add_u32 s26, s72, s30
	s_addc_u32 s27, s73, 0
	s_add_u32 s28, s74, s30
	s_addc_u32 s29, s75, 0
	s_add_u32 s94, s94, 0x2000
	s_and_b32 s94, s94, 0x3ffff
	global_load_dwordx4 v[106:109], v184, s[26:27] offset:-4096 nt
	global_load_dwordx4 v[118:121], v184, s[28:29] offset:-4096 nt
	global_load_dwordx4 v[138:141], v184, s[26:27] nt
	global_load_dwordx4 v[142:145], v184, s[28:29] nt
	s_add_u32 s30, s95, s94
	s_add_u32 s26, s72, s30
	s_addc_u32 s27, s73, 0
	s_add_u32 s28, s74, s30
	s_addc_u32 s29, s75, 0
	s_add_u32 s94, s94, 0x2000
	s_and_b32 s94, s94, 0x3ffff
	global_load_dwordx4 v[146:149], v184, s[26:27] offset:-4096 nt
	global_load_dwordx4 v[150:153], v184, s[28:29] offset:-4096 nt
	global_load_dwordx4 v[154:157], v184, s[26:27] nt
	global_load_dwordx4 v[158:161], v184, s[28:29] nt
	s_add_u32 s30, s95, s94
	s_add_u32 s26, s72, s30
	s_addc_u32 s27, s73, 0
	s_add_u32 s28, s74, s30
	s_addc_u32 s29, s75, 0
	s_add_u32 s94, s94, 0x2000
	s_and_b32 s94, s94, 0x3ffff
	global_load_dwordx4 v[162:165], v184, s[26:27] offset:-4096 nt
	global_load_dwordx4 v[166:169], v184, s[28:29] offset:-4096 nt
	global_load_dwordx4 v[170:173], v184, s[26:27] nt
	global_load_dwordx4 v[174:177], v184, s[28:29] nt
.LBB0_596:
	s_cmp_eq_u32 s24, 15
	s_cbranch_scc1 .Lsp_last_b
	s_add_i32 s25, s24, 1
	s_lshr_b32 s30, s25, 2
	s_cmp_lt_u32 s30, 2
	s_cselect_b32 s95, s98, s100
	s_cselect_b32 s97, s99, s101
	s_bitcmp1_b32 s30, 0
	s_cselect_b32 s95, s97, s95
	s_lshl_b32 s95, s95, 18
	s_add_u32 s95, s95, 0x1000
	s_waitcnt vmcnt(28)
	v_cvt_pk_bf16_f32 v240, v18, v19
	v_cvt_pk_bf16_f32 v241, v20, v21
	ds_write_b64 v190, v[240:241]
	v_cvt_pk_bf16_f32 v180, v22, v23
	v_cvt_pk_bf16_f32 v181, v24, v25
	ds_write_b64 v191, v[180:181] offset:8192
	v_cvt_pk_bf16_f32 v240, v26, v27
	v_cvt_pk_bf16_f32 v241, v28, v29
	ds_write_b64 v192, v[240:241]
	v_cvt_pk_bf16_f32 v180, v34, v35
	v_cvt_pk_bf16_f32 v181, v36, v37
	ds_write_b64 v193, v[180:181] offset:8192
	s_add_u32 s30, s95, s94
	s_add_u32 s26, s72, s30
	s_addc_u32 s27, s73, 0
	s_add_u32 s28, s74, s30
	s_addc_u32 s29, s75, 0
	s_add_u32 s94, s94, 0x2000
	s_and_b32 s94, s94, 0x3ffff
	global_load_dwordx4 v[18:21], v184, s[26:27] offset:-4096 nt
	global_load_dwordx4 v[22:25], v184, s[28:29] offset:-4096 nt
	global_load_dwordx4 v[26:29], v184, s[26:27] nt
	global_load_dwordx4 v[34:37], v184, s[28:29] nt
	s_waitcnt vmcnt(28)
	v_cvt_pk_bf16_f32 v240, v30, v31
	v_cvt_pk_bf16_f32 v241, v32, v33
	ds_write_b64 v194, v[240:241]
	v_cvt_pk_bf16_f32 v180, v38, v39
	v_cvt_pk_bf16_f32 v181, v40, v41
	ds_write_b64 v195, v[180:181] offset:8192
	v_cvt_pk_bf16_f32 v240, v42, v43
	v_cvt_pk_bf16_f32 v241, v44, v45
	ds_write_b64 v197, v[240:241]
	v_cvt_pk_bf16_f32 v180, v50, v51
	v_cvt_pk_bf16_f32 v181, v52, v53
	ds_write_b64 v198, v[180:181] offset:8192
	s_add_u32 s30, s95, s94
	s_add_u32 s26, s72, s30
	s_addc_u32 s27, s73, 0
	s_add_u32 s28, s74, s30
	s_addc_u32 s29, s75, 0
	s_add_u32 s94, s94, 0x2000
	s_and_b32 s94, s94, 0x3ffff
	global_load_dwordx4 v[30:33], v184, s[26:27] offset:-4096 nt
	global_load_dwordx4 v[38:41], v184, s[28:29] offset:-4096 nt
	global_load_dwordx4 v[42:45], v184, s[26:27] nt
	global_load_dwordx4 v[50:53], v184, s[28:29] nt
	s_waitcnt vmcnt(28)
	v_cvt_pk_bf16_f32 v240, v46, v47
	v_cvt_pk_bf16_f32 v241, v48, v49
	ds_write_b64 v199, v[240:241]
	v_cvt_pk_bf16_f32 v180, v54, v55
	v_cvt_pk_bf16_f32 v181, v56, v57
	ds_write_b64 v200, v[180:181] offset:8192
	v_cvt_pk_bf16_f32 v240, v58, v59
	v_cvt_pk_bf16_f32 v241, v60, v61
	ds_write_b64 v201, v[240:241]
	v_cvt_pk_bf16_f32 v180, v66, v67
	v_cvt_pk_bf16_f32 v181, v68, v69
	ds_write_b64 v202, v[180:181] offset:8192
	s_add_u32 s30, s95, s94
	s_add_u32 s26, s72, s30
	s_addc_u32 s27, s73, 0
	s_add_u32 s28, s74, s30
	s_addc_u32 s29, s75, 0
	s_add_u32 s94, s94, 0x2000
	s_and_b32 s94, s94, 0x3ffff
	global_load_dwordx4 v[46:49], v184, s[26:27] offset:-4096 nt
	global_load_dwordx4 v[54:57], v184, s[28:29] offset:-4096 nt
	global_load_dwordx4 v[58:61], v184, s[26:27] nt
	global_load_dwordx4 v[66:69], v184, s[28:29] nt
	s_waitcnt vmcnt(28)
	v_cvt_pk_bf16_f32 v240, v62, v63
	v_cvt_pk_bf16_f32 v241, v64, v65
	ds_write_b64 v203, v[240:241]
	v_cvt_pk_bf16_f32 v180, v70, v71
	v_cvt_pk_bf16_f32 v181, v72, v73
	ds_write_b64 v204, v[180:181] offset:8192
	v_cvt_pk_bf16_f32 v240, v74, v75
	v_cvt_pk_bf16_f32 v241, v76, v77
	ds_write_b64 v205, v[240:241]
	v_cvt_pk_bf16_f32 v180, v82, v83
	v_cvt_pk_bf16_f32 v181, v84, v85
	ds_write_b64 v206, v[180:181] offset:8192
	s_add_u32 s30, s95, s94
	s_add_u32 s26, s72, s30
	s_addc_u32 s27, s73, 0
	s_add_u32 s28, s74, s30
	s_addc_u32 s29, s75, 0
	s_add_u32 s94, s94, 0x2000
	s_and_b32 s94, s94, 0x3ffff
	global_load_dwordx4 v[62:65], v184, s[26:27] offset:-4096 nt
	global_load_dwordx4 v[70:73], v184, s[28:29] offset:-4096 nt
	global_load_dwordx4 v[74:77], v184, s[26:27] nt
	global_load_dwordx4 v[82:85], v184, s[28:29] nt
	s_waitcnt vmcnt(28)
	v_cvt_pk_bf16_f32 v240, v78, v79
	v_cvt_pk_bf16_f32 v241, v80, v81
	ds_write_b64 v190, v[240:241] offset:4096
	v_cvt_pk_bf16_f32 v180, v86, v87
	v_cvt_pk_bf16_f32 v181, v88, v89
	ds_write_b64 v191, v[180:181] offset:12288
	v_cvt_pk_bf16_f32 v240, v90, v91
	v_cvt_pk_bf16_f32 v241, v92, v93
	ds_write_b64 v207, v[240:241]
	v_cvt_pk_bf16_f32 v180, v110, v111
	v_cvt_pk_bf16_f32 v181, v112, v113
	ds_write_b64 v208, v[180:181] offset:8192
	s_add_u32 s30, s95, s94
	s_add_u32 s26, s72, s30
	s_addc_u32 s27, s73, 0
	s_add_u32 s28, s74, s30
	s_addc_u32 s29, s75, 0
	s_add_u32 s94, s94, 0x2000
	s_and_b32 s94, s94, 0x3ffff
	global_load_dwordx4 v[78:81], v184, s[26:27] offset:-4096 nt
	global_load_dwordx4 v[86:89], v184, s[28:29] offset:-4096 nt
	global_load_dwordx4 v[90:93], v184, s[26:27] nt
	global_load_dwordx4 v[110:113], v184, s[28:29] nt
	s_waitcnt vmcnt(28)
	v_cvt_pk_bf16_f32 v240, v106, v107
	v_cvt_pk_bf16_f32 v241, v108, v109
	ds_write_b64 v209, v[240:241]
	v_cvt_pk_bf16_f32 v180, v118, v119
	v_cvt_pk_bf16_f32 v181, v120, v121
	ds_write_b64 v210, v[180:181] offset:8192
	v_cvt_pk_bf16_f32 v240, v138, v139
	v_cvt_pk_bf16_f32 v241, v140, v141
	ds_write_b64 v211, v[240:241]
	v_cvt_pk_bf16_f32 v180, v142, v143
	v_cvt_pk_bf16_f32 v181, v144, v145
	ds_write_b64 v212, v[180:181] offset:8192
	s_add_u32 s30, s95, s94
	s_add_u32 s26, s72, s30
	s_addc_u32 s27, s73, 0
	s_add_u32 s28, s74, s30
	s_addc_u32 s29, s75, 0
	s_add_u32 s94, s94, 0x2000
	s_and_b32 s94, s94, 0x3ffff
	global_load_dwordx4 v[106:109], v184, s[26:27] offset:-4096 nt
	global_load_dwordx4 v[118:121], v184, s[28:29] offset:-4096 nt
	global_load_dwordx4 v[138:141], v184, s[26:27] nt
	global_load_dwordx4 v[142:145], v184, s[28:29] nt
	s_waitcnt vmcnt(28)
	v_cvt_pk_bf16_f32 v240, v146, v147
	v_cvt_pk_bf16_f32 v241, v148, v149
	ds_write_b64 v213, v[240:241]
	v_cvt_pk_bf16_f32 v180, v150, v151
	v_cvt_pk_bf16_f32 v181, v152, v153
	ds_write_b64 v214, v[180:181] offset:8192
	v_cvt_pk_bf16_f32 v240, v154, v155
	v_cvt_pk_bf16_f32 v241, v156, v157
	ds_write_b64 v215, v[240:241]
	v_cvt_pk_bf16_f32 v180, v158, v159
	v_cvt_pk_bf16_f32 v181, v160, v161
	ds_write_b64 v216, v[180:181] offset:8192
	s_add_u32 s30, s95, s94
	s_add_u32 s26, s72, s30
	s_addc_u32 s27, s73, 0
	s_add_u32 s28, s74, s30
	s_addc_u32 s29, s75, 0
	s_add_u32 s94, s94, 0x2000
	s_and_b32 s94, s94, 0x3ffff
	global_load_dwordx4 v[146:149], v184, s[26:27] offset:-4096 nt
	global_load_dwordx4 v[150:153], v184, s[28:29] offset:-4096 nt
	global_load_dwordx4 v[154:157], v184, s[26:27] nt
	global_load_dwordx4 v[158:161], v184, s[28:29] nt
	s_waitcnt vmcnt(28)
	v_cvt_pk_bf16_f32 v240, v162, v163
	v_cvt_pk_bf16_f32 v241, v164, v165
	ds_write_b64 v217, v[240:241]
	v_cvt_pk_bf16_f32 v180, v166, v167
	v_cvt_pk_bf16_f32 v181, v168, v169
	ds_write_b64 v218, v[180:181] offset:8192
	v_cvt_pk_bf16_f32 v240, v170, v171
	v_cvt_pk_bf16_f32 v241, v172, v173
	ds_write_b64 v219, v[240:241]
	v_cvt_pk_bf16_f32 v180, v174, v175
	v_cvt_pk_bf16_f32 v181, v176, v177
	ds_write_b64 v220, v[180:181] offset:8192
	s_add_u32 s30, s95, s94
	s_add_u32 s26, s72, s30
	s_addc_u32 s27, s73, 0
	s_add_u32 s28, s74, s30
	s_addc_u32 s29, s75, 0
	s_add_u32 s94, s94, 0x2000
	s_and_b32 s94, s94, 0x3ffff
	global_load_dwordx4 v[162:165], v184, s[26:27] offset:-4096 nt
	global_load_dwordx4 v[166:169], v184, s[28:29] offset:-4096 nt
	global_load_dwordx4 v[170:173], v184, s[26:27] nt
	global_load_dwordx4 v[174:177], v184, s[28:29] nt
	s_branch .LBB0_600
.Lsp_last_b:
	s_waitcnt vmcnt(29)
	v_cvt_pk_bf16_f32 v240, v26, v27
	v_cvt_pk_bf16_f32 v241, v28, v29
	ds_write_b64 v192, v[240:241]
	s_waitcnt vmcnt(27)
	v_cvt_pk_bf16_f32 v240, v34, v35
	v_cvt_pk_bf16_f32 v241, v36, v37
	ds_write_b64 v193, v[240:241] offset:8192
	v_cvt_pk_bf16_f32 v240, v30, v31
	v_cvt_pk_bf16_f32 v241, v32, v33
	ds_write_b64 v194, v[240:241]
	s_waitcnt vmcnt(26)
	v_cvt_pk_bf16_f32 v240, v38, v39
	v_cvt_pk_bf16_f32 v241, v40, v41
	ds_write_b64 v195, v[240:241] offset:8192
	s_waitcnt vmcnt(25)
	v_cvt_pk_bf16_f32 v240, v42, v43
	v_cvt_pk_bf16_f32 v241, v44, v45
	ds_write_b64 v197, v[240:241]
	s_waitcnt vmcnt(23)
	v_cvt_pk_bf16_f32 v240, v50, v51
	v_cvt_pk_bf16_f32 v241, v52, v53
	ds_write_b64 v198, v[240:241] offset:8192
	v_cvt_pk_bf16_f32 v240, v46, v47
	v_cvt_pk_bf16_f32 v241, v48, v49
	ds_write_b64 v199, v[240:241]
	s_waitcnt vmcnt(22)
	v_cvt_pk_bf16_f32 v240, v54, v55
	v_cvt_pk_bf16_f32 v241, v56, v57
	ds_write_b64 v200, v[240:241] offset:8192
	s_waitcnt vmcnt(21)
	v_cvt_pk_bf16_f32 v240, v58, v59
	v_cvt_pk_bf16_f32 v241, v60, v61
	ds_write_b64 v201, v[240:241]
	s_waitcnt vmcnt(19)
	v_cvt_pk_bf16_f32 v240, v66, v67
	v_cvt_pk_bf16_f32 v241, v68, v69
	ds_write_b64 v202, v[240:241] offset:8192
	v_cvt_pk_bf16_f32 v240, v62, v63
	v_cvt_pk_bf16_f32 v241, v64, v65
	ds_write_b64 v203, v[240:241]
	s_waitcnt vmcnt(18)
	v_cvt_pk_bf16_f32 v240, v70, v71
	v_cvt_pk_bf16_f32 v241, v72, v73
	ds_write_b64 v204, v[240:241] offset:8192
	s_waitcnt vmcnt(17)
	v_cvt_pk_bf16_f32 v240, v74, v75
	v_cvt_pk_bf16_f32 v241, v76, v77
	ds_write_b64 v205, v[240:241]
	s_waitcnt vmcnt(15)
	v_cvt_pk_bf16_f32 v240, v82, v83
	v_cvt_pk_bf16_f32 v241, v84, v85
	v_cvt_pk_bf16_f32 v180, v18, v19
	v_cvt_pk_bf16_f32 v181, v20, v21
	ds_write_b64 v206, v[240:241] offset:8192
	v_cvt_pk_bf16_f32 v240, v78, v79
	v_cvt_pk_bf16_f32 v241, v80, v81
	v_cvt_pk_bf16_f32 v238, v22, v23
	v_cvt_pk_bf16_f32 v239, v24, v25
	ds_write2st64_b64 v190, v[180:181], v[240:241] offset1:8
	s_waitcnt vmcnt(14)
	v_cvt_pk_bf16_f32 v180, v86, v87
	v_cvt_pk_bf16_f32 v181, v88, v89
	ds_write2st64_b64 v191, v[238:239], v[180:181] offset0:16 offset1:24
	s_waitcnt vmcnt(13)
	v_cvt_pk_bf16_f32 v180, v90, v91
	v_cvt_pk_bf16_f32 v181, v92, v93
	ds_write_b64 v207, v[180:181]
	s_waitcnt vmcnt(11)
	v_cvt_pk_bf16_f32 v180, v110, v111
	v_cvt_pk_bf16_f32 v181, v112, v113
	ds_write_b64 v208, v[180:181] offset:8192
	v_cvt_pk_bf16_f32 v180, v106, v107
	v_cvt_pk_bf16_f32 v181, v108, v109
	ds_write_b64 v209, v[180:181]
	s_waitcnt vmcnt(10)
	v_cvt_pk_bf16_f32 v180, v118, v119
	v_cvt_pk_bf16_f32 v181, v120, v121
	ds_write_b64 v210, v[180:181] offset:8192
	s_waitcnt vmcnt(9)
	v_cvt_pk_bf16_f32 v180, v138, v139
	v_cvt_pk_bf16_f32 v181, v140, v141
	ds_write_b64 v211, v[180:181]
	s_waitcnt vmcnt(7)
	v_cvt_pk_bf16_f32 v180, v142, v143
	v_cvt_pk_bf16_f32 v181, v144, v145
	ds_write_b64 v212, v[180:181] offset:8192
	v_cvt_pk_bf16_f32 v180, v146, v147
	v_cvt_pk_bf16_f32 v181, v148, v149
	ds_write_b64 v213, v[180:181]
	s_waitcnt vmcnt(6)
	v_cvt_pk_bf16_f32 v180, v150, v151
	v_cvt_pk_bf16_f32 v181, v152, v153
	ds_write_b64 v214, v[180:181] offset:8192
	s_waitcnt vmcnt(5)
	v_cvt_pk_bf16_f32 v180, v154, v155
	v_cvt_pk_bf16_f32 v181, v156, v157
	ds_write_b64 v215, v[180:181]
	s_waitcnt vmcnt(3)
	v_cvt_pk_bf16_f32 v180, v158, v159
	v_cvt_pk_bf16_f32 v181, v160, v161
	ds_write_b64 v216, v[180:181] offset:8192
	v_cvt_pk_bf16_f32 v180, v162, v163
	v_cvt_pk_bf16_f32 v181, v164, v165
	ds_write_b64 v217, v[180:181]
	s_waitcnt vmcnt(2)
	v_cvt_pk_bf16_f32 v180, v166, v167
	v_cvt_pk_bf16_f32 v181, v168, v169
	ds_write_b64 v218, v[180:181] offset:8192
	s_waitcnt vmcnt(1)
	v_cvt_pk_bf16_f32 v180, v170, v171
	v_cvt_pk_bf16_f32 v181, v172, v173
	s_add_i32 s25, s24, 1
	ds_write_b64 v219, v[180:181]
	s_waitcnt vmcnt(0)
	v_cvt_pk_bf16_f32 v180, v174, v175
	v_cvt_pk_bf16_f32 v181, v176, v177
	s_cmp_lg_u32 s24, 15
	ds_write_b64 v220, v[180:181] offset:8192
	s_cbranch_scc0 .LBB0_598
.LBB0_598:
	s_and_b32 s26, s24, 3
	s_cmp_eq_u32 s26, 0
	s_cselect_b64 s[26:27], -1, 0
	s_cmp_lt_u32 s24, 12
	s_cselect_b64 s[28:29], -1, 0
	s_and_b64 s[26:27], s[26:27], s[28:29]
	s_andn2_b64 vcc, exec, s[26:27]
	s_cbranch_vccnz .LBB0_600
.LBB0_600:
	ds_read_b128 v[238:241], v221
	ds_read_b128 v[242:245], v227
	s_add_i32 s22, s22, 32
	s_cmp_eq_u32 s25, 16
	s_waitcnt lgkmcnt(1)
	v_mfma_f32_16x16x32_bf16 v[238:241], v[238:241], v[2:5], 0
	ds_read_b128 v[248:251], v227 offset:4096
	s_waitcnt lgkmcnt(1)
	v_mfma_f32_16x16x32_bf16 v[238:241], v[242:245], v[10:13], v[238:241]
	ds_read_b128 v[242:245], v228
	s_waitcnt lgkmcnt(0)
	v_mfma_f32_16x16x32_bf16 v[238:241], v[242:245], v[6:9], v[238:241]
	ds_read_b128 v[242:245], v229
	s_waitcnt lgkmcnt(0)
	v_mfma_f32_16x16x32_bf16 v[240:243], v[242:245], v[14:17], v[238:241]
	ds_read_b128 v[244:247], v221 offset:4096
	s_nop 6
	v_max_f32_e32 v179, v241, v241
	v_max_f32_e32 v180, v240, v240
	v_max_f32_e32 v179, v180, v179
	s_waitcnt lgkmcnt(0)
	v_mfma_f32_16x16x32_bf16 v[244:247], v[244:247], v[2:5], 0
	v_max_f32_e32 v180, v243, v243
	v_max_f32_e32 v181, v242, v242
	v_max_f32_e32 v180, v181, v180
	v_mfma_f32_16x16x32_bf16 v[244:247], v[248:251], v[10:13], v[244:247]
	ds_read_b128 v[248:251], v228 offset:4096
	s_waitcnt lgkmcnt(0)
	v_mfma_f32_16x16x32_bf16 v[244:247], v[248:251], v[6:9], v[244:247]
	ds_read_b128 v[248:251], v229 offset:4096
	s_waitcnt lgkmcnt(0)
	v_mfma_f32_16x16x32_bf16 v[244:247], v[248:251], v[14:17], v[244:247]
	s_nop 7
	v_max_f32_e32 v181, v247, v247
	v_max_f32_e32 v186, v246, v246
	v_max_f32_e32 v181, v186, v181
	v_max3_f32 v181, v244, v245, v181
	v_max3_f32 v179, v179, v180, v181
	v_mov_b32_e32 v180, v179
	s_nop 1
	v_permlane16_swap_b32_e32 v179, v180
	v_max_f32_e32 v180, v180, v180
	v_max_f32_e32 v179, v179, v179
	v_max_f32_e32 v179, v179, v180
	v_mov_b32_e32 v180, v179
	s_nop 1
	v_permlane32_swap_b32_e32 v179, v180
	v_max3_f32 v238, v178, v179, v180
	v_sub_f32_e32 v178, v178, v238
	v_exp_f32_e32 v186, v178
	v_sub_f32_e32 v181, v243, v238
	v_sub_f32_e32 v180, v242, v238
	v_sub_f32_e32 v179, v241, v238
	v_sub_f32_e32 v178, v240, v238
	v_sub_f32_e32 v239, v247, v238
	v_sub_f32_e32 v242, v246, v238
	v_sub_f32_e32 v241, v245, v238
	v_sub_f32_e32 v240, v244, v238
	v_exp_f32_e32 v178, v178
	v_exp_f32_e32 v179, v179
	v_exp_f32_e32 v180, v180
	v_exp_f32_e32 v181, v181
	v_exp_f32_e32 v240, v240
	v_exp_f32_e32 v241, v241
	v_exp_f32_e32 v242, v242
	v_exp_f32_e32 v243, v239
	v_pk_mul_f32 v[136:137], v[136:137], v[186:187] op_sel_hi:[1,0]
	v_pk_add_f32 v[246:247], v[178:179], v[240:241]
	v_cvt_pk_bf16_f32 v178, v178, v179
	v_pk_add_f32 v[244:245], v[180:181], v[242:243]
	v_cvt_pk_bf16_f32 v179, v180, v181
	v_cvt_pk_bf16_f32 v180, v240, v241
	v_cvt_pk_bf16_f32 v181, v242, v243
	ds_read_b64_tr_b16 v[240:241], v230 offset:8192
	ds_read_b64_tr_b16 v[242:243], v230 offset:12288
	v_pk_mul_f32 v[134:135], v[134:135], v[186:187] op_sel_hi:[1,0]
	v_pk_mul_f32 v[132:133], v[132:133], v[186:187] op_sel_hi:[1,0]
	v_pk_mul_f32 v[130:131], v[130:131], v[186:187] op_sel_hi:[1,0]
	s_waitcnt lgkmcnt(0)
	v_mfma_f32_16x16x32_bf16 v[134:137], v[240:243], v[178:181], v[134:137]
	ds_read_b64_tr_b16 v[240:241], v231 offset:8192
	ds_read_b64_tr_b16 v[242:243], v231 offset:12288
	v_pk_mul_f32 v[128:129], v[128:129], v[186:187] op_sel_hi:[1,0]
	v_pk_mul_f32 v[126:127], v[126:127], v[186:187] op_sel_hi:[1,0]
	s_waitcnt lgkmcnt(0)
	v_mfma_f32_16x16x32_bf16 v[130:133], v[240:243], v[178:181], v[130:133]
	ds_read_b64_tr_b16 v[240:241], v232 offset:8192
	ds_read_b64_tr_b16 v[242:243], v232 offset:12288
	v_pk_mul_f32 v[124:125], v[124:125], v[186:187] op_sel_hi:[1,0]
	v_pk_mul_f32 v[122:123], v[122:123], v[186:187] op_sel_hi:[1,0]
	s_waitcnt lgkmcnt(0)
	v_mfma_f32_16x16x32_bf16 v[126:129], v[240:243], v[178:181], v[126:129]
	ds_read_b64_tr_b16 v[240:241], v233 offset:8192
	ds_read_b64_tr_b16 v[242:243], v233 offset:12288
	v_pk_mul_f32 v[116:117], v[116:117], v[186:187] op_sel_hi:[1,0]
	v_pk_mul_f32 v[114:115], v[114:115], v[186:187] op_sel_hi:[1,0]
	s_waitcnt lgkmcnt(0)
	v_mfma_f32_16x16x32_bf16 v[122:125], v[240:243], v[178:181], v[122:125]
	ds_read_b64_tr_b16 v[240:241], v234 offset:8192
	ds_read_b64_tr_b16 v[242:243], v234 offset:12288
	v_pk_mul_f32 v[104:105], v[104:105], v[186:187] op_sel_hi:[1,0]
	v_pk_mul_f32 v[102:103], v[102:103], v[186:187] op_sel_hi:[1,0]
	s_waitcnt lgkmcnt(0)
	v_mfma_f32_16x16x32_bf16 v[114:117], v[240:243], v[178:181], v[114:117]
	ds_read_b64_tr_b16 v[240:241], v235 offset:8192
	ds_read_b64_tr_b16 v[242:243], v235 offset:12288
	v_pk_mul_f32 v[100:101], v[100:101], v[186:187] op_sel_hi:[1,0]
	v_pk_mul_f32 v[98:99], v[98:99], v[186:187] op_sel_hi:[1,0]
	s_waitcnt lgkmcnt(0)
	v_mfma_f32_16x16x32_bf16 v[102:105], v[240:243], v[178:181], v[102:105]
	ds_read_b64_tr_b16 v[240:241], v236 offset:8192
	ds_read_b64_tr_b16 v[242:243], v236 offset:12288
	v_pk_mul_f32 v[96:97], v[96:97], v[186:187] op_sel_hi:[1,0]
	v_pk_mul_f32 v[94:95], v[94:95], v[186:187] op_sel_hi:[1,0]
	s_waitcnt lgkmcnt(0)
	v_mfma_f32_16x16x32_bf16 v[98:101], v[240:243], v[178:181], v[98:101]
	ds_read_b64_tr_b16 v[240:241], v237 offset:8192
	ds_read_b64_tr_b16 v[242:243], v237 offset:12288
	v_pk_mov_b32 v[248:249], v[246:247], v[244:245] op_sel:[1,0]
	v_mov_b32_e32 v247, v245
	s_waitcnt lgkmcnt(0)
	v_mfma_f32_16x16x32_bf16 v[94:97], v[240:243], v[178:181], v[94:97]
	v_add_f32_e64 v244, v248, v246
	v_add_f32_e64 v245, v249, v247
	v_add_f32_e32 v239, v244, v245
	v_fmac_f32_e32 v239, v189, v186
	s_cbranch_scc1 .LBB0_602
	v_mov_b32_e32 v189, v239
	v_mov_b32_e32 v178, v238
	s_mov_b32 s24, s25
	s_branch .LBB0_596
